# v22 + static s_setprio 1 for waves 4-7 during the attention phase (no priority control there before), reset at phase end
# speedup vs baseline: 1.0080x; 1.0004x over previous
; #define LAS __attribute__((address_space(3)))
; __device__ __forceinline__ Frame fresh(const Frame& F0) { Frame F = F0; int t = threadIdx.x; asm volatile("" : "+v"(t)); F.tid = t; F.lane = t & 63; F.wave = __builtin_amdgcn_readfirstlane(t >> 6); return F; }
; __device__ __forceinline__ void fx_attn_unit(const Args& A, Frame& F, int bh, int qb, float qkmax) {
;     LAS unsigned char* Kb = F.lds; LAS unsigned char* Vb = F.lds + 36864; LAS float* Gb = (LAS float*)(F.lds + 73728);
;     const int lane = F.lane, wave = F.wave, tid = F.tid;
;     const int hh = lane >> 5, l31 = lane & 31, i16 = lane & 15, q = i16 >> 2, p = i16 & 3, blk = (lane >> 4) & 1;
;     const int b = bh >> 4, hd = bh & 15, q0 = qb * 256;
;     const bf16* Qg = (const bf16*)(A.ws + WS_BIG) + (size_t)b * SEQ * 4096 + hd * 64;
;     const bf16* Kg = Qg + 1024; const bf16* Vg = Qg + 2048; const bf16* Og = Qg + 3072;
;     const float* FLp = (const float*)(A.ws + WS_FL) + (size_t)bh * SEQ; const float* FTp = (const float*)(A.ws + WS_FT) + bh * 128;
;     const int tq = q0 + 32 * wave + l31;
;     LAS unsigned char* Qw = F.lds + 86016 + wave * 4096 + lane * 16;
; #pragma unroll
;     for (int ks = 0; ks < 4; ++ks) *(LAS u32x4*)(Qw + ks * 1024) = *(const u32x4*)(Qg + (size_t)tq * 4096 + 16 * ks + 8 * hh);
;     float Gw;
;     float l = 0.f; f32x16 o0, o1;
; #pragma unroll
;     for (int e = 0; e < 16; ++e) { o0[e] = 0.f; o1[e] = 0.f; }
;     const int NT = 4 * qb + 4;
;     const int ss_ = tid >> 3, ch = tid & 7;
; __device__ __forceinline__ void fx_phase_attn(const Args& A, Frame& F0) {
;     Frame F = fresh(F0);
;     float qkmax;
;     { const float gq = wave_max(fabsf(A.fx_qn_g[F.lane])), gk = wave_max(fabsf(A.fx_kn_g[F.lane])); qkmax = 8.0f * 8.0f * 0.125f * LOG2E * gq * gk * 1.02f + 0.5f; }
;     unsigned* qctr = (unsigned*)(A.ws + WS_BAR) + 4096;
;     volatile LAS unsigned* slot = (volatile LAS unsigned*)(F.lds + 73728 + 8192);
.LBB0_671:
	s_or_b64 exec, exec, s[4:5]
	v_mov_b32_e32 v2, v182
	s_waitcnt lgkmcnt(0)
	s_barrier
	v_readlane_b32 s4, v253, 5
	v_and_b32_e32 v110, 63, v2
	v_lshlrev_b32_e32 v0, 2, v110
	v_readlane_b32 s18, v253, 19
	v_readlane_b32 s19, v253, 20
	v_cmp_lt_i32_e32 vcc, v192, v186
	v_readfirstlane_b32 s0, v2
	s_ashr_i32 s1, s0, 6
	s_cmp_lt_u32 s1, 4
	s_cbranch_scc1 .Lattn_prio_done
	s_setprio 1
.Lattn_prio_done:
	v_cndmask_b32_e32 v5, v185, v192, vcc
	v_lshlrev_b32_e32 v5, 2, v5
	global_load_dword v3, v0, s[18:19]
	v_cmp_lt_i32_e32 vcc, v198, v186
	global_load_dword v0, v0, s[36:37]
	v_readlane_b32 s5, v253, 6
	s_mov_b32 s0, 0x3f828f5c
	v_ashrrev_i32_e32 v178, 3, v2
	s_movk_i32 s5, 0x90
	s_lshl_b32 s4, s1, 5
	v_readlane_b32 s6, v253, 7
	v_readlane_b32 s7, v253, 8
	v_readlane_b32 s8, v253, 9
	v_readlane_b32 s9, v253, 10
	v_readlane_b32 s10, v253, 11
	v_readlane_b32 s11, v253, 12
	v_readlane_b32 s12, v253, 13
	v_readlane_b32 s13, v253, 14
	v_readlane_b32 s14, v253, 15
	v_readlane_b32 s15, v253, 16
	v_readlane_b32 s16, v253, 17
	v_readlane_b32 s17, v253, 18
	v_and_b32_e32 v115, 31, v2
	v_cmp_eq_u32_e64 s[6:7], 0, v2
	v_or_b32_e32 v179, 64, v110
	v_cmp_eq_u32_e64 s[8:9], 0, v110
	v_cmp_gt_u32_e64 s[10:11], 2, v110
	v_cmp_gt_u32_e64 s[12:13], 4, v110
	v_cmp_gt_u32_e64 s[14:15], 8, v110
	v_cmp_gt_u32_e64 s[16:17], 16, v110
	v_cmp_gt_u32_e64 s[18:19], 32, v110
	v_lshl_or_b32 v204, v185, 2, v196
	v_mul_u32_u24_e32 v205, 0x90, v115
	v_or_b32_e32 v213, 0x100, v110
	s_waitcnt vmcnt(0)
	v_and_b32_e32 v4, 0x7fffffff, v3
	ds_bpermute_b32 v4, v5, v4
	v_max_f32_e64 v3, |v3|, |v3|
	s_waitcnt lgkmcnt(0)
	v_max_f32_e32 v4, v4, v4
	v_max_f32_e32 v3, v3, v4
	v_cndmask_b32_e32 v4, v185, v198, vcc
	v_lshlrev_b32_e32 v4, 2, v4
	ds_bpermute_b32 v6, v4, v3
	v_cmp_lt_i32_e32 vcc, v252, v186
	s_waitcnt lgkmcnt(0)
	v_max_f32_e32 v6, v6, v6
	v_max_f32_e32 v3, v3, v6
	v_cndmask_b32_e32 v6, v185, v252, vcc
	v_lshlrev_b32_e32 v6, 2, v6
	ds_bpermute_b32 v7, v6, v3
	v_cmp_lt_i32_e32 vcc, v189, v186
	s_waitcnt lgkmcnt(0)
	v_max_f32_e32 v7, v7, v7
	v_max_f32_e32 v3, v3, v7
	v_cndmask_b32_e32 v7, v185, v189, vcc
	v_lshlrev_b32_e32 v7, 2, v7
	ds_bpermute_b32 v8, v7, v3
	v_cmp_lt_i32_e32 vcc, v188, v186
	s_waitcnt lgkmcnt(0)
	v_max_f32_e32 v8, v8, v8
	v_max_f32_e32 v3, v3, v8
	v_cndmask_b32_e32 v8, v185, v188, vcc
	v_lshlrev_b32_e32 v8, 2, v8
	ds_bpermute_b32 v9, v8, v3
	v_cmp_lt_i32_e32 vcc, v187, v186
	s_waitcnt lgkmcnt(0)
	v_max_f32_e32 v9, v9, v9
	v_max_f32_e32 v3, v3, v9
	v_cndmask_b32_e32 v9, v185, v187, vcc
	v_lshlrev_b32_e32 v111, 2, v9
	ds_bpermute_b32 v9, v111, v3
	s_waitcnt lgkmcnt(0)
	v_max_f32_e32 v9, v9, v9
	v_max_f32_e32 v3, v3, v9
	v_and_b32_e32 v9, 0x7fffffff, v0
	ds_bpermute_b32 v5, v5, v9
	v_max_f32_e64 v0, |v0|, |v0|
	v_mul_f32_e32 v3, 0x4138aa3b, v3
	s_waitcnt lgkmcnt(0)
	v_max_f32_e32 v5, v5, v5
	v_max_f32_e32 v0, v0, v5
	ds_bpermute_b32 v4, v4, v0
	v_lshrrev_b32_e32 v5, 2, v2
	s_waitcnt lgkmcnt(0)
	v_max_f32_e32 v4, v4, v4
	v_max_f32_e32 v0, v0, v4
	ds_bpermute_b32 v4, v6, v0
	v_and_b32_e32 v6, 7, v2
	v_lshlrev_b32_e32 v112, 3, v6
	v_lshlrev_b32_e32 v6, 4, v6
	s_waitcnt lgkmcnt(0)
	v_max_f32_e32 v4, v4, v4
	v_max_f32_e32 v0, v0, v4
	ds_bpermute_b32 v4, v7, v0
	v_add_u32_e32 v7, -1, v185
	v_cmp_lt_i32_e32 vcc, v7, v194
	s_waitcnt lgkmcnt(0)
	v_max_f32_e32 v4, v4, v4
	v_max_f32_e32 v0, v0, v4
	ds_bpermute_b32 v4, v8, v0
	v_cndmask_b32_e32 v7, v7, v185, vcc
	v_lshlrev_b32_e32 v180, 2, v7
	v_add_u32_e32 v7, -2, v185
	v_cmp_lt_i32_e32 vcc, v7, v194
	s_waitcnt lgkmcnt(0)
	v_max_f32_e32 v4, v4, v4
	v_max_f32_e32 v0, v0, v4
	v_cndmask_b32_e32 v7, v7, v185, vcc
	v_lshlrev_b32_e32 v181, 2, v7
	v_add_u32_e32 v7, -4, v185
	v_cmp_lt_i32_e32 vcc, v7, v194
	ds_bpermute_b32 v4, v111, v0
	s_waitcnt lgkmcnt(0)
	v_max_f32_e32 v4, v4, v4
	v_cndmask_b32_e32 v7, v7, v185, vcc
	v_lshlrev_b32_e32 v200, 2, v7
	v_add_u32_e32 v7, -8, v185
	v_cmp_lt_i32_e32 vcc, v7, v194
	v_max_f32_e32 v0, v0, v4
	v_mul_f32_e32 v0, v3, v0
	v_cndmask_b32_e32 v7, v7, v185, vcc
	v_lshlrev_b32_e32 v201, 2, v7
	v_add_u32_e32 v7, -16, v185
	v_cmp_lt_i32_e32 vcc, v7, v194
	v_bfe_u32 v4, v2, 5, 1
	v_fma_f32 v113, v0, s0, 0.5
	v_cndmask_b32_e32 v7, v7, v185, vcc
	v_lshlrev_b32_e32 v202, 2, v7
	v_subrev_u32_e32 v7, 32, v185
	v_cmp_lt_i32_e32 vcc, v7, v194
	s_lshl_b32 s0, s1, 12
	v_lshlrev_b32_e32 v114, 2, v4
	v_cndmask_b32_e32 v7, v7, v185, vcc
	s_add_i32 s0, s0, 0
	v_lshlrev_b32_e32 v0, 3, v4
	v_lshlrev_b32_e32 v203, 2, v7
	v_mul_lo_u32 v7, v178, s5
	s_lshl_b32 s5, s1, 8
	s_add_i32 s1, 0, 0x12000
	v_lshlrev_b32_e32 v206, 4, v4
	v_and_or_b32 v4, v5, 3, v114
	v_lshlrev_b32_e32 v5, 1, v2
	s_add_i32 s0, s0, 0x15000
	v_lshlrev_b32_e32 v3, 4, v110
	s_add_i32 s44, s1, s5
	v_and_b32_e32 v207, 32, v5
	v_lshlrev_b32_e32 v5, 3, v2
	v_and_b32_e32 v208, 24, v5
	v_mul_u32_u24_e32 v209, 0x90, v4
	s_ashr_i32 s5, s4, 31
	v_add3_u32 v210, 0, v7, v6
	v_lshl_add_u32 v211, v2, 2, s1
	v_add_u32_e32 v212, s44, v206
	v_lshlrev_b32_e32 v116, 1, v0
	v_add_u32_e32 v214, s0, v3
	s_branch .LBB0_674

; __device__ __forceinline__ void xcd_barrier(const XcdBarrier& b) {
;     asm volatile("s_waitcnt vmcnt(0)" ::: "memory");
;     __syncthreads();
;     if (threadIdx.x == 0) {
;         unsigned* bar = b.bar;
;         __builtin_amdgcn_s_waitcnt(0);
;         unsigned nloc = b.st[0], nx = b.st[1];
;         if (nloc == 0u) { xcd_barrier_complete(bar, b.x, nloc, nx); b.st[0] = nloc; b.st[1] = nx; }
.LBB0_719:
	s_setprio 0
	v_readlane_b32 s44, v253, 0
	v_readlane_b32 s45, v253, 1
	v_readlane_b32 s33, v253, 2
	s_waitcnt vmcnt(0)
	s_barrier
	s_mov_b64 s[4:5], exec
	v_readlane_b32 s0, v253, 3
	v_readlane_b32 s1, v253, 4
	s_and_b64 s[0:1], s[4:5], s[0:1]
	s_mov_b64 exec, s[0:1]
	s_cbranch_execz .LBB0_763
	v_readlane_b32 s0, v254, 51
	s_waitcnt vmcnt(0) expcnt(0) lgkmcnt(0)
	s_nop 0
	v_mov_b32_e32 v0, s0
	ds_read_b32 v2, v0
	v_readlane_b32 s0, v254, 52
	s_waitcnt lgkmcnt(0)
	v_cmp_ne_u32_e32 vcc, 0, v2
	v_mov_b32_e32 v0, s0
	ds_read_b32 v0, v0
	s_cbranch_vccnz .LBB0_734
	s_add_u32 s0, s44, 0x1000
	s_addc_u32 s1, s45, 0
	s_add_u32 s6, s44, 0x1100
	s_addc_u32 s7, s45, 0
	s_add_u32 s8, s44, 0x1200
	s_addc_u32 s9, s45, 0
	s_add_u32 s10, s44, 0x1300
	s_addc_u32 s11, s45, 0
	s_mov_b32 s30, 1
	s_mov_b64 s[12:13], 0
	s_branch .LBB0_724
